# attention unit: sink-logit load hoisted to the top of the unit (was issued after the Q tile wait and then waited vmcnt(0)); QK k-step 3 K reads hoisted too
# speedup vs baseline: 1.0275x; 1.0004x over previous
; #define LAS __attribute__((address_space(3)))
; __device__ __forceinline__ void attn_unit(const bf16* proj, unsigned char* ws, LAS unsigned char* lds, int a) {
;     ...
;     const int gb = a >> 2, kvh = (a >> 1) & 1, hp = a & 1;
;     int n, nb; if (gb < 64) { nb = 32; n = gb & 31; } else { nb = 16; n = (gb - 64) & 15; }
;     const int tok0 = gb * 128, hw = wave >> 2, rq = wave & 3, fr = lane & 15, fq = lane >> 4;
;     const int h0 = kvh * 4 + hp * 2, h = h0 + hw;
;     LAS unsigned char* QS = lds + LQ; LAS unsigned char* KS = lds + LK; LAS unsigned char* VS = lds + LV;
;     const int kb0 = (n > 0) ? n - 1 : 0, kb1 = (n + 1 < nb) ? n + 1 : nb - 1;
;     v4u kr[4], vr[4];
;     {
;         v4u q0[4], q1[4];
;         tile_ld(q0, proj, tok0, C_Q + h0 * 128, tid); tile_ld(q1, proj, tok0, C_Q + (h0 + 1) * 128, tid);
;         tile_ld(kr, proj, tok0 + (kb0 - n) * 128, C_K + kvh * 128, tid); tile_ld(vr, proj, tok0 + (kb0 - n) * 128, C_V + kvh * 128, tid);
;         __syncthreads();
;         tile_st<QK_STRIDE>(q0, QS, tid); tile_st<QK_STRIDE>(q1, QS + 128 * QK_STRIDE, tid);
;     }
;     const LAS unsigned char* qbase = QS + hw * (128 * QK_STRIDE) + (rq * 32 + fr) * QK_STRIDE + (8 * fq) * 2;
;     const float sk2 = par[PAR_SINK + h] * LOG2E;
;     float mrow[2], lrow[2]; mrow[0] = mrow[1] = sk2; lrow[0] = lrow[1] = (fq == 0) ? 1.0f : 0.0f;
;     f32x4 O[2][8];
; #pragma unroll
;     for (int rt = 0; rt < 2; ++rt)
; #pragma unroll
;         for (int dt = 0; dt < 8; ++dt) O[rt][dt] = (f32x4){0.f, 0.f, 0.f, 0.f};
; #pragma unroll 1
;     for (int kb = kb0; kb <= kb1; ++kb) {
;         if (kb != kb0) __syncthreads();
;         tile_st<QK_STRIDE>(kr, KS, tid); tile_st<V_STRIDE>(vr, VS, tid);
;         __syncthreads();
;         if (kb < kb1) { tile_ld(kr, proj, tok0 + (kb + 1 - n) * 128, C_K + kvh * 128, tid); tile_ld(vr, proj, tok0 + (kb + 1 - n) * 128, C_V + kvh * 128, tid); }
.LBB0_603:
	s_ashr_i32 s4, s68, 2
	s_bfe_u32 s5, s68, 0x10001
	s_cmp_lt_i32 s4, 64
	v_mov_b32_e32 v33, v160
	s_cselect_b32 s13, 31, 15
	s_lshl_b32 s3, s68, 1
	s_lshl_b32 s2, s5, 2
	v_readfirstlane_b32 s1, v33
	s_and_b32 s3, s3, 2
	s_and_b32 s69, s13, s4
	s_ashr_i32 s0, s1, 8
	s_or_b32 s2, s2, s3
	s_lshl_b32 s44, s4, 7
	s_add_i32 s50, s0, s2
	s_ashr_i32 s73, s50, 31
	s_mov_b32 s72, s50
	s_lshl_b64 s[72:73], s[72:73], 2
	s_add_u32 s72, s28, s72
	s_addc_u32 s73, s29, s73
	v_mov_b32_e32 v47, 0x200000
	global_load_dword v49, v47, s[72:73] offset:1024
	s_add_i32 s51, s69, 1
	s_lshl_b32 s2, s2, 8
	v_ashrrev_i32_e32 v34, 4, v33
	s_add_u32 s2, s26, s2
	v_lshlrev_b32_e32 v0, 4, v33
	v_add_u32_e32 v48, s44, v34
	s_addc_u32 s3, s27, 0
	v_and_b32_e32 v162, 0xf0, v0
	s_waitcnt lgkmcnt(0)
	v_lshl_add_u64 v[0:1], s[2:3], 0, v[162:163]
	v_add_u32_e32 v4, 32, v48
	v_add_u32_e32 v6, 64, v48
	v_add_u32_e32 v8, 0x60, v48
	v_mad_i64_i32 v[2:3], s[2:3], v48, s60, v[0:1]
	v_mad_i64_i32 v[4:5], s[2:3], v4, s60, v[0:1]
	v_mad_i64_i32 v[6:7], s[2:3], v6, s60, v[0:1]
	v_mad_i64_i32 v[0:1], s[2:3], v8, s60, v[0:1]
	v_sub_u32_e64 v35, s69, 1 clamp
	s_sub_i32 s2, s4, s69
	global_load_dwordx4 v[38:41], v[2:3], off
	global_load_dwordx4 v[42:45], v[2:3], off offset:256
	global_load_dwordx4 v[50:53], v[4:5], off
	global_load_dwordx4 v[54:57], v[4:5], off offset:256
	global_load_dwordx4 v[58:61], v[6:7], off
	global_load_dwordx4 v[62:65], v[6:7], off offset:256
	global_load_dwordx4 v[66:69], v[0:1], off
	global_load_dwordx4 v[70:73], v[0:1], off offset:256
	v_add_u32_e32 v0, s2, v35
	s_lshl_b32 s2, s5, 8
	s_add_u32 s2, s26, s2
	v_lshl_add_u32 v0, v0, 7, v34
	s_addc_u32 s3, s27, 0
	v_lshl_add_u64 v[164:165], s[2:3], 0, v[162:163]
	v_add_u32_e32 v1, 32, v0
	v_mad_i64_i32 v[4:5], s[2:3], v0, s60, v[164:165]
	v_mad_i64_i32 v[12:13], s[2:3], v1, s60, v[164:165]
	v_add_u32_e32 v1, 64, v0
	v_add_u32_e32 v0, 0x60, v0
	v_mad_i64_i32 v[20:21], s[2:3], v1, s60, v[164:165]
	s_waitcnt vmcnt(24)
	v_mad_i64_i32 v[28:29], s[2:3], v0, s60, v[164:165]
	global_load_dwordx4 v[0:3], v[4:5], off offset:2048
	s_nop 0
	global_load_dwordx4 v[4:7], v[4:5], off offset:2560
	s_nop 0
	global_load_dwordx4 v[8:11], v[12:13], off offset:2048
	s_nop 0
	global_load_dwordx4 v[12:15], v[12:13], off offset:2560
	s_nop 0
	global_load_dwordx4 v[16:19], v[20:21], off offset:2048
	s_nop 0
	global_load_dwordx4 v[20:23], v[20:21], off offset:2560
	s_nop 0
	global_load_dwordx4 v[24:27], v[28:29], off offset:2048
	s_nop 0
	global_load_dwordx4 v[28:31], v[28:29], off offset:2560
	v_bfe_u32 v37, v33, 4, 2
	s_lshr_b32 s1, s1, 1
	s_min_u32 s71, s51, s13
	v_and_b32_e32 v36, 15, v33
	v_mul_lo_u32 v32, v34, s64
	v_cmp_eq_u32_e64 s[2:3], 0, v37
	s_and_b32 s1, s1, 0x60
	v_cmp_ge_u32_e32 vcc, s71, v35
	v_cndmask_b32_e64 v174, 0, 1.0, s[2:3]
	v_add3_u32 v46, 0, v162, v32
	v_readfirstlane_b32 s70, v35
	v_or_b32_e32 v172, s1, v36
	s_mov_b64 s[4:5], -1
	s_and_b64 vcc, exec, vcc
	v_lshlrev_b32_e32 v175, 2, v37
	s_barrier
	s_waitcnt vmcnt(15)
	ds_write_b128 v46, v[38:41]
	s_waitcnt vmcnt(13)
	ds_write_b128 v46, v[50:53] offset:8704
	s_waitcnt vmcnt(11)
	ds_write_b128 v46, v[58:61] offset:17408
	s_waitcnt vmcnt(9)
	ds_write_b128 v46, v[66:69] offset:26112
	ds_write_b128 v46, v[42:45] offset:34816
	ds_write_b128 v46, v[54:57] offset:43520
	ds_write_b128 v46, v[62:65] offset:52224
	s_waitcnt vmcnt(8)
	ds_write_b128 v46, v[70:73] offset:60928
	s_cbranch_vccz .LBB0_615
	s_mul_i32 s0, s0, 0x8800
	s_ashr_i32 s51, s50, 31
	s_add_i32 s4, s0, 0
	s_lshl_b64 s[0:1], s[50:51], 2
	s_add_u32 s0, s28, s0
	s_addc_u32 s1, s29, s1
	v_mov_b32_e32 v35, 0x200000
	s_nop 0
	v_mbcnt_hi_u32_b32 v173, -1, v161
	v_and_b32_e32 v53, 64, v173
	v_lshlrev_b32_e32 v50, 4, v37
	v_xor_b32_e32 v178, 16, v173
	v_add_u32_e32 v180, 64, v53
	v_add_u32_e32 v35, s65, v162
	v_add_u32_e32 v38, s66, v162
	v_lshlrev_b32_e32 v162, 2, v37
	v_lshrrev_b32_e32 v37, 2, v36
	v_mul_u32_u24_e32 v51, 0x110, v36
	v_add_u32_e32 v52, s65, v50
	v_xor_b32_e32 v177, 32, v173
	v_cmp_lt_i32_e32 vcc, v178, v180
	v_lshlrev_b32_e32 v33, 3, v33
	v_or_b32_e32 v54, v162, v37
	v_mov_b32_e32 v56, s4
	v_add_u32_e32 v201, v52, v51
	v_cndmask_b32_e32 v52, v173, v178, vcc
	v_cmp_lt_i32_e32 vcc, v177, v180
	s_min_u32 s0, s69, 1
	v_mul_lo_u32 v34, v34, s62
	v_mov_b32_e32 v44, 0
	v_and_b32_e32 v55, 24, v33
	v_sub_u32_e32 v181, v162, v172
	v_mul_u32_u24_e32 v53, 0x120, v54
	v_mad_u32_u24 v51, v172, s64, v56
	v_cndmask_b32_e32 v54, v173, v177, vcc
	s_lshl_b32 s72, s0, 7
	s_mov_b32 s51, 0
	v_mov_b32_e32 v179, v174
	v_mov_b32_e32 v176, v174
	v_add_u32_e32 v182, v35, v32
	v_add_u32_e32 v183, v38, v34
	v_mov_b32_e32 v45, v44
	v_mov_b32_e32 v46, v44
	v_mov_b32_e32 v47, v44
	v_mov_b32_e32 v40, v44
	v_mov_b32_e32 v41, v44
	v_mov_b32_e32 v42, v44
	v_mov_b32_e32 v43, v44
	v_mov_b32_e32 v32, v44
	v_mov_b32_e32 v33, v44
	v_mov_b32_e32 v34, v44
	v_mov_b32_e32 v35, v44
	v_mov_b32_e32 v36, v44
	v_mov_b32_e32 v37, v44
	v_mov_b32_e32 v38, v44
	v_mov_b32_e32 v39, v44
	v_mov_b32_e32 v96, v44
	v_mov_b32_e32 v97, v44
	v_mov_b32_e32 v98, v44
	v_mov_b32_e32 v99, v44
	v_mov_b32_e32 v88, v44
	v_mov_b32_e32 v89, v44
	v_sub_u32_e32 v184, -2, v181
	v_add_u32_e32 v185, 0x70, v181
	v_sub_u32_e32 v186, 0xffffff90, v181
	v_add_u32_e32 v187, 0x71, v181
	v_sub_u32_e32 v188, 0xffffff8f, v181
	v_add_u32_e32 v189, 0x72, v181
	v_sub_u32_e32 v190, 0xffffff8e, v181
	v_add_u32_e32 v191, 0x73, v181
	v_sub_u32_e32 v192, 0xffffff8d, v181
	v_add_u32_e32 v193, -16, v181
	v_sub_u32_e32 v194, 16, v181
	v_add_u32_e32 v195, -15, v181
	v_sub_u32_e32 v196, 15, v181
	v_add_u32_e32 v197, -14, v181
	v_sub_u32_e32 v198, 14, v181
	v_add_u32_e32 v199, -13, v181
	v_sub_u32_e32 v200, 13, v181
	v_add3_u32 v202, s66, v55, v53
	v_lshlrev_b32_e32 v203, 2, v52
	v_lshlrev_b32_e32 v204, 2, v54
	v_add_u32_e32 v205, v51, v50
	v_subrev_u32_e32 v206, s72, v48
	v_mov_b32_e32 v90, v44
	v_mov_b32_e32 v91, v44
	v_mov_b32_e32 v80, v44
	s_waitcnt vmcnt(8)
	v_mul_f32_e32 v209, 0x3fb8aa3b, v49
	v_mov_b32_e32 v208, v209
	v_mov_b32_e32 v81, v44
	v_mov_b32_e32 v82, v44
	v_mov_b32_e32 v83, v44
	v_mov_b32_e32 v76, v44
	v_mov_b32_e32 v77, v44
	v_mov_b32_e32 v78, v44
	v_mov_b32_e32 v79, v44
	v_mov_b32_e32 v72, v44
	v_mov_b32_e32 v73, v44
	v_mov_b32_e32 v74, v44
	v_mov_b32_e32 v75, v44
	v_mov_b32_e32 v68, v44
	v_mov_b32_e32 v69, v44
	v_mov_b32_e32 v70, v44
	v_mov_b32_e32 v71, v44
	v_mov_b32_e32 v60, v44
	v_mov_b32_e32 v61, v44
	v_mov_b32_e32 v62, v44
	v_mov_b32_e32 v63, v44
	v_mov_b32_e32 v64, v44
	v_mov_b32_e32 v65, v44
	v_mov_b32_e32 v66, v44
	v_mov_b32_e32 v67, v44
	v_mov_b32_e32 v48, v44
	v_mov_b32_e32 v49, v44
	v_mov_b32_e32 v50, v44
	v_mov_b32_e32 v51, v44
	v_mov_b32_e32 v52, v44
	v_mov_b32_e32 v53, v44
	v_mov_b32_e32 v54, v44
	v_mov_b32_e32 v55, v44
	v_mov_b32_e32 v56, v44
	v_mov_b32_e32 v57, v44
	v_mov_b32_e32 v58, v44
	v_mov_b32_e32 v59, v44
	v_mov_b32_e32 v84, v44
	v_mov_b32_e32 v85, v44
	v_mov_b32_e32 v86, v44
	v_mov_b32_e32 v87, v44
	s_cmp_eq_u32 s51, 0
	s_cbranch_scc1 .LBB0_606

; #define LAS __attribute__((address_space(3)))
; __device__ __forceinline__ void attn_unit(const bf16* proj, unsigned char* ws, LAS unsigned char* lds, int a) {
;     ...
; #pragma unroll
;         for (int s = 0; s < 4; ++s) {
;             const bf16x8 qa = *(const LAS bf16x8*)(qbase + 64 * s), qb = *(const LAS bf16x8*)(qbase + 16 * QK_STRIDE + 64 * s);
; #pragma unroll
;             for (int kt = 0; kt < 8; ++kt) {
;                 const bf16x8 kf = *(const LAS bf16x8*)(KS + (16 * kt + fr) * QK_STRIDE + (32 * s + 8 * fq) * 2);
;                 st[0][kt] = __builtin_amdgcn_mfma_f32_16x16x32_bf16(kf, qa, st[0][kt], 0, 0, 0);
;                 st[1][kt] = __builtin_amdgcn_mfma_f32_16x16x32_bf16(kf, qb, st[1][kt], 0, 0, 0);
;             }
;         }
.LBB0_608:
	ds_read_b128 v[92:95], v205
	ds_read_b128 v[100:103], v205 offset:4352
	ds_read_b128 v[104:107], v201
	ds_read_b128 v[112:115], v201 offset:4352
	ds_read_b128 v[120:123], v201 offset:8704
	ds_read_b128 v[128:131], v201 offset:13056
	ds_read_b128 v[136:139], v201 offset:17408
	ds_read_b128 v[144:147], v201 offset:21760
	ds_read_b128 v[152:155], v201 offset:26112
	ds_read_b128 v[210:213], v201 offset:30464
	s_waitcnt lgkmcnt(7)
	v_mfma_f32_16x16x32_bf16 v[108:111], v[104:107], v[92:95], 0
	s_cmp_lg_u32 s72, s51
	s_cselect_b64 s[56:57], -1, 0
	s_cmp_lt_u32 s70, s69
	v_mfma_f32_16x16x32_bf16 v[104:107], v[104:107], v[100:103], 0
	s_cselect_b64 s[4:5], -1, 0
	v_sub_u32_e32 v207, 0, v181
	v_cndmask_b32_e64 v207, v207, v181, s[4:5]
	s_waitcnt lgkmcnt(6)
	v_mfma_f32_16x16x32_bf16 v[116:119], v[112:115], v[92:95], 0
	s_cmp_eq_u32 s72, s51
	v_mfma_f32_16x16x32_bf16 v[112:115], v[112:115], v[100:103], 0
	s_waitcnt lgkmcnt(5)
	v_mfma_f32_16x16x32_bf16 v[124:127], v[120:123], v[92:95], 0
	v_mfma_f32_16x16x32_bf16 v[120:123], v[120:123], v[100:103], 0
	s_waitcnt lgkmcnt(4)
	v_mfma_f32_16x16x32_bf16 v[132:135], v[128:131], v[92:95], 0
	v_mfma_f32_16x16x32_bf16 v[128:131], v[128:131], v[100:103], 0
	s_waitcnt lgkmcnt(3)
	v_mfma_f32_16x16x32_bf16 v[140:143], v[136:139], v[92:95], 0
	v_mfma_f32_16x16x32_bf16 v[136:139], v[136:139], v[100:103], 0
	ds_read_b128 v[246:249], v201 offset:64
	s_waitcnt lgkmcnt(3)
	v_mfma_f32_16x16x32_bf16 v[148:151], v[144:147], v[92:95], 0
	v_mfma_f32_16x16x32_bf16 v[144:147], v[144:147], v[100:103], 0
	ds_read_b128 v[250:253], v201 offset:4416
	s_waitcnt lgkmcnt(3)
	v_mfma_f32_16x16x32_bf16 v[156:159], v[152:155], v[92:95], 0
	v_mfma_f32_16x16x32_bf16 v[152:155], v[152:155], v[100:103], 0
	ds_read_b128 v[218:221], v201 offset:8768
	s_waitcnt lgkmcnt(3)
	v_mfma_f32_16x16x32_bf16 v[92:95], v[210:213], v[92:95], 0
	v_mfma_f32_16x16x32_bf16 v[100:103], v[210:213], v[100:103], 0
	ds_read_b128 v[210:213], v205 offset:64
	ds_read_b128 v[214:217], v205 offset:4416
	ds_read_b128 v[238:241], v201 offset:13120
	s_waitcnt lgkmcnt(2)
	v_mfma_f32_16x16x32_bf16 v[108:111], v[246:249], v[210:213], v[108:111]
	s_waitcnt lgkmcnt(1)
	v_mfma_f32_16x16x32_bf16 v[104:107], v[246:249], v[214:217], v[104:107]
	ds_read_b128 v[246:249], v201 offset:17472
	v_mfma_f32_16x16x32_bf16 v[116:119], v[250:253], v[210:213], v[116:119]
	v_mfma_f32_16x16x32_bf16 v[112:115], v[250:253], v[214:217], v[112:115]
	ds_read_b128 v[250:253], v201 offset:21824
	v_mfma_f32_16x16x32_bf16 v[124:127], v[218:221], v[210:213], v[124:127]
	v_mfma_f32_16x16x32_bf16 v[120:123], v[218:221], v[214:217], v[120:123]
	ds_read_b128 v[218:221], v201 offset:26176
	s_waitcnt lgkmcnt(3)
	v_mfma_f32_16x16x32_bf16 v[132:135], v[238:241], v[210:213], v[132:135]
	v_mfma_f32_16x16x32_bf16 v[128:131], v[238:241], v[214:217], v[128:131]
	ds_read_b128 v[238:241], v201 offset:30528
	s_waitcnt lgkmcnt(3)
	v_mfma_f32_16x16x32_bf16 v[140:143], v[246:249], v[210:213], v[140:143]
	v_mfma_f32_16x16x32_bf16 v[136:139], v[246:249], v[214:217], v[136:139]
	ds_read_b128 v[246:249], v201 offset:128
	s_waitcnt lgkmcnt(3)
	v_mfma_f32_16x16x32_bf16 v[148:151], v[250:253], v[210:213], v[148:151]
	v_mfma_f32_16x16x32_bf16 v[144:147], v[250:253], v[214:217], v[144:147]
	ds_read_b128 v[250:253], v201 offset:4480
	s_waitcnt lgkmcnt(3)
	v_mfma_f32_16x16x32_bf16 v[156:159], v[218:221], v[210:213], v[156:159]
	v_mfma_f32_16x16x32_bf16 v[152:155], v[218:221], v[214:217], v[152:155]
	ds_read_b128 v[218:221], v201 offset:8832
	s_waitcnt lgkmcnt(3)
	v_mfma_f32_16x16x32_bf16 v[92:95], v[238:241], v[210:213], v[92:95]
	v_mfma_f32_16x16x32_bf16 v[100:103], v[238:241], v[214:217], v[100:103]
	ds_read_b128 v[210:213], v205 offset:128
	ds_read_b128 v[214:217], v205 offset:4480
	ds_read_b128 v[238:241], v201 offset:13184
	s_waitcnt lgkmcnt(2)
	v_mfma_f32_16x16x32_bf16 v[108:111], v[246:249], v[210:213], v[108:111]
	s_waitcnt lgkmcnt(1)
	v_mfma_f32_16x16x32_bf16 v[104:107], v[246:249], v[214:217], v[104:107]
	ds_read_b128 v[246:249], v201 offset:17536
	v_mfma_f32_16x16x32_bf16 v[116:119], v[250:253], v[210:213], v[116:119]
	v_mfma_f32_16x16x32_bf16 v[112:115], v[250:253], v[214:217], v[112:115]
	ds_read_b128 v[250:253], v201 offset:21888
	v_mfma_f32_16x16x32_bf16 v[124:127], v[218:221], v[210:213], v[124:127]
	v_mfma_f32_16x16x32_bf16 v[120:123], v[218:221], v[214:217], v[120:123]
	ds_read_b128 v[242:245], v201 offset:26240
	s_waitcnt lgkmcnt(3)
	v_mfma_f32_16x16x32_bf16 v[222:225], v[238:241], v[210:213], v[132:135]
	s_nop 2
	v_mfma_f32_16x16x32_bf16 v[128:131], v[238:241], v[214:217], v[128:131]
	s_waitcnt lgkmcnt(2)
	v_mfma_f32_16x16x32_bf16 v[218:221], v[246:249], v[210:213], v[140:143]
	v_mfma_f32_16x16x32_bf16 v[226:229], v[246:249], v[214:217], v[136:139]
	ds_read_b128 v[246:249], v201 offset:30592
	s_waitcnt lgkmcnt(2)
; #define LAS __attribute__((address_space(3)))
; __device__ __forceinline__ void attn_unit(const bf16* proj, unsigned char* ws, LAS unsigned char* lds, int a) {
;     ...
; #pragma unroll
;         for (int s = 0; s < 4; ++s) {
;             const bf16x8 qa = *(const LAS bf16x8*)(qbase + 64 * s), qb = *(const LAS bf16x8*)(qbase + 16 * QK_STRIDE + 64 * s);
; #pragma unroll
;             for (int kt = 0; kt < 8; ++kt) {
;                 const bf16x8 kf = *(const LAS bf16x8*)(KS + (16 * kt + fr) * QK_STRIDE + (32 * s + 8 * fq) * 2);
;                 st[0][kt] = __builtin_amdgcn_mfma_f32_16x16x32_bf16(kf, qa, st[0][kt], 0, 0, 0);
;                 st[1][kt] = __builtin_amdgcn_mfma_f32_16x16x32_bf16(kf, qb, st[1][kt], 0, 0, 0);
;             }
;         }
;         bf16x8 pb[2][4];
; #pragma unroll
;         for (int rt = 0; rt < 2; ++rt) {
;             const int qi = rq * 32 + rt * 16 + fr;
;             if (kb != n) {
;                 const int sgn = (kb < n) ? 1 : -1, dbase = sgn * (4 * fq - qi);
; #pragma unroll
;                 for (int kt = 0; kt < 8; ++kt)
; #pragma unroll
;                     for (int r = 0; r < 4; ++r) { const int dd = dbase + sgn * (16 * kt + r); st[rt][kt][r] += __builtin_bit_cast(float, (unsigned)(dd >> 31) & 0xF149F2CAu); }
;             }
	v_mfma_f32_16x16x32_bf16 v[148:151], v[250:253], v[210:213], v[148:151]
	v_mfma_f32_16x16x32_bf16 v[230:233], v[250:253], v[214:217], v[144:147]
	ds_read_b128 v[250:253], v201 offset:192
	s_waitcnt lgkmcnt(2)
	v_mfma_f32_16x16x32_bf16 v[156:159], v[242:245], v[210:213], v[156:159]
	v_mfma_f32_16x16x32_bf16 v[234:237], v[242:245], v[214:217], v[152:155]
	s_waitcnt lgkmcnt(1)
	v_mfma_f32_16x16x32_bf16 v[214:217], v[246:249], v[214:217], v[100:103]
	ds_read_b128 v[238:241], v205 offset:192
	ds_read_b128 v[242:245], v205 offset:4544
	s_nop 0
	s_waitcnt lgkmcnt(0)
	v_mfma_f32_16x16x32_bf16 v[140:143], v[250:253], v[242:245], v[104:107]
	s_nop 2
	v_mfma_f32_16x16x32_bf16 v[210:213], v[246:249], v[210:213], v[92:95]
	ds_read_b128 v[246:249], v201 offset:4544
	v_mfma_f32_16x16x32_bf16 v[92:95], v[250:253], v[238:241], v[108:111]
	s_nop 2
	ds_read_b128 v[250:253], v201 offset:8896
	s_waitcnt lgkmcnt(1)
	v_mfma_f32_16x16x32_bf16 v[136:139], v[246:249], v[242:245], v[112:115]
	s_nop 2
	v_mfma_f32_16x16x32_bf16 v[100:103], v[246:249], v[238:241], v[116:119]
	ds_read_b128 v[246:249], v201 offset:13248
	s_waitcnt lgkmcnt(1)
	v_mfma_f32_16x16x32_bf16 v[104:107], v[250:253], v[238:241], v[124:127]
	v_mfma_f32_16x16x32_bf16 v[132:135], v[250:253], v[242:245], v[120:123]
	ds_read_b128 v[250:253], v201 offset:17600
	s_waitcnt lgkmcnt(1)
	v_mfma_f32_16x16x32_bf16 v[108:111], v[246:249], v[238:241], v[222:225]
	v_mfma_f32_16x16x32_bf16 v[128:131], v[246:249], v[242:245], v[128:131]
	ds_read_b128 v[246:249], v201 offset:21952
	s_waitcnt lgkmcnt(1)
	v_mfma_f32_16x16x32_bf16 v[144:147], v[250:253], v[238:241], v[218:221]
	v_mfma_f32_16x16x32_bf16 v[124:127], v[250:253], v[242:245], v[226:229]
	ds_read_b128 v[250:253], v201 offset:26304
	s_waitcnt lgkmcnt(1)
	v_mfma_f32_16x16x32_bf16 v[148:151], v[246:249], v[238:241], v[148:151]
	v_mfma_f32_16x16x32_bf16 v[120:123], v[246:249], v[242:245], v[230:233]
	ds_read_b128 v[246:249], v201 offset:30656
	s_waitcnt lgkmcnt(1)
	v_mfma_f32_16x16x32_bf16 v[152:155], v[250:253], v[238:241], v[156:159]
	v_mfma_f32_16x16x32_bf16 v[116:119], v[250:253], v[242:245], v[234:237]
	s_waitcnt lgkmcnt(0)
	v_mfma_f32_16x16x32_bf16 v[156:159], v[246:249], v[238:241], v[210:213]
	s_nop 2
	v_mfma_f32_16x16x32_bf16 v[112:115], v[246:249], v[242:245], v[214:217]
	s_nop 3
	s_cbranch_scc1 .LBB0_610
	s_cmp_lt_u32 s70, s69
	s_cbranch_scc0 .Lam_a_next
	v_cmp_gt_i32_e32 vcc, 0, v181
	v_cndmask_b32_e32 v92, v92, v171, vcc
	v_cmp_gt_i32_e32 vcc, -1, v181
	v_cndmask_b32_e32 v93, v93, v171, vcc
	v_cmp_gt_i32_e32 vcc, -2, v181
	v_cndmask_b32_e32 v94, v94, v171, vcc
	v_cmp_gt_i32_e32 vcc, -3, v181
	v_cndmask_b32_e32 v95, v95, v171, vcc
	v_cmp_gt_i32_e32 vcc, -16, v181
	v_cndmask_b32_e32 v100, v100, v171, vcc
	v_cmp_gt_i32_e32 vcc, 0xffffffef, v181
	v_cndmask_b32_e32 v101, v101, v171, vcc
	v_cmp_gt_i32_e32 vcc, 0xffffffee, v181
	v_cndmask_b32_e32 v102, v102, v171, vcc
	v_cmp_gt_i32_e32 vcc, 0xffffffed, v181
	v_cndmask_b32_e32 v103, v103, v171, vcc
	v_cmp_gt_i32_e32 vcc, 0xffffffe0, v181
	v_cndmask_b32_e32 v104, v104, v171, vcc
	v_cmp_gt_i32_e32 vcc, 0xffffffdf, v181
	v_cndmask_b32_e32 v105, v105, v171, vcc
	v_cmp_gt_i32_e32 vcc, 0xffffffde, v181
	v_cndmask_b32_e32 v106, v106, v171, vcc
	v_cmp_gt_i32_e32 vcc, 0xffffffdd, v181
	v_cndmask_b32_e32 v107, v107, v171, vcc
	v_cmp_gt_i32_e32 vcc, 0xffffffd0, v181
	v_cndmask_b32_e32 v108, v108, v171, vcc
	v_cmp_gt_i32_e32 vcc, 0xffffffcf, v181
	v_cndmask_b32_e32 v109, v109, v171, vcc
	v_cmp_gt_i32_e32 vcc, 0xffffffce, v181
	v_cndmask_b32_e32 v110, v110, v171, vcc
	v_cmp_gt_i32_e32 vcc, 0xffffffcd, v181
	v_cndmask_b32_e32 v111, v111, v171, vcc
	v_cmp_gt_i32_e32 vcc, 0xffffffc0, v181
	v_cndmask_b32_e32 v144, v144, v171, vcc
	v_cmp_gt_i32_e32 vcc, 0xffffffbf, v181
	v_cndmask_b32_e32 v145, v145, v171, vcc
	v_cmp_gt_i32_e32 vcc, 0xffffffbe, v181
	v_cndmask_b32_e32 v146, v146, v171, vcc
	v_cmp_gt_i32_e32 vcc, 0xffffffbd, v181
	v_cndmask_b32_e32 v147, v147, v171, vcc
	v_cmp_gt_i32_e32 vcc, 0xffffffb0, v181
	v_cndmask_b32_e32 v148, v148, v171, vcc
	v_cmp_gt_i32_e32 vcc, 0xffffffaf, v181
	v_cndmask_b32_e32 v149, v149, v171, vcc
	v_cmp_gt_i32_e32 vcc, 0xffffffae, v181
	v_cndmask_b32_e32 v150, v150, v171, vcc
	v_cmp_gt_i32_e32 vcc, 0xffffffad, v181
	v_cndmask_b32_e32 v151, v151, v171, vcc
	v_cmp_gt_i32_e32 vcc, 0xffffffa0, v181
	v_cndmask_b32_e32 v152, v152, v171, vcc
	v_cmp_gt_i32_e32 vcc, 0xffffff9f, v181
	v_cndmask_b32_e32 v153, v153, v171, vcc
	v_cmp_gt_i32_e32 vcc, 0xffffff9e, v181
	v_cndmask_b32_e32 v154, v154, v171, vcc
	v_cmp_gt_i32_e32 vcc, 0xffffff9d, v181
	v_cndmask_b32_e32 v155, v155, v171, vcc
	v_cmp_gt_i32_e32 vcc, 0xffffff90, v181
	v_cndmask_b32_e32 v156, v156, v171, vcc
	v_cmp_gt_i32_e32 vcc, 0xffffff8f, v181
	v_cndmask_b32_e32 v157, v157, v171, vcc
	v_cmp_gt_i32_e32 vcc, 0xffffff8e, v181
	v_cndmask_b32_e32 v158, v158, v171, vcc
	v_cmp_gt_i32_e32 vcc, 0xffffff8d, v181
	v_cndmask_b32_e32 v159, v159, v171, vcc
	s_branch .LBB0_610
